# add: sample_task warms its conv inputs (state_conv / PROJ q,k,v,z rows) with 7 pattern-matched loads per task
# speedup vs baseline: 1.0120x; 1.0120x over previous
.LBB0_980:
	s_mul_hi_i32 s0, s8, 0x2aaaaaab
	s_lshr_b32 s1, s0, 31
	s_ashr_i32 s85, s0, 2
	s_add_i32 s85, s85, s1
	s_mul_i32 s0, s85, 24
	s_sub_i32 s96, s8, s0
	s_lshl_b32 s90, s96, 7
	v_or_b32_e32 v82, s90, v138
	s_mul_i32 s84, s85, 3
	v_ashrrev_i32_e32 v83, 31, v82
	v_mov_b32_e32 v153, v233
	v_lshl_add_u64 v[4:5], v[82:83], 2, s[76:77]
	v_add_u32_e32 v80, s84, v139
	v_min_u32_e32 v246, 2, v139
	v_add_u32_e32 v246, s84, v246
	v_mad_i64_i32 v[248:249], vcc, v246, s7, v[4:5]
	global_load_dword v237, v[248:249], off
	s_mov_b64 s[98:99], 0x3000
	v_lshl_add_u64 v[248:249], v[248:249], 0, s[98:99]
	global_load_dword v237, v[248:249], off
	v_lshl_add_u64 v[248:249], v[248:249], 0, s[98:99]
	global_load_dword v237, v[248:249], off
	s_lshl_b32 s100, s85, 3
	s_addk_i32 s100, 0x2000
	v_add_u32_e32 v246, s100, v139
	v_mov_b64_e32 v[248:249], s[86:87]
	v_mad_i64_i32 v[248:249], vcc, v246, s9, v[248:249]
	v_lshl_add_u64 v[248:249], v[82:83], 1, v[248:249]
	global_load_dword v237, v[248:249], off offset:2048
	s_mov_b64 s[98:99], 0x1800
	v_lshl_add_u64 v[248:249], v[248:249], 0, s[98:99]
	global_load_dword v237, v[248:249], off offset:2048
	v_lshl_add_u64 v[248:249], v[248:249], 0, s[98:99]
	global_load_dword v237, v[248:249], off offset:2048
	v_lshl_add_u64 v[248:249], v[248:249], 0, s[98:99]
	global_load_dword v237, v[248:249], off offset:2048
	s_and_saveexec_b64 s[0:1], s[14:15]
	s_xor_b64 s[0:1], exec, s[0:1]
	s_cbranch_execz .LBB0_982
	v_mad_i64_i32 v[0:1], vcc, v80, s7, v[4:5]
	global_load_dwordx4 v[10:13], v[0:1], off
	global_load_dwordx4 v[16:19], v[0:1], off offset:16
	global_load_dwordx4 v[20:23], v[0:1], off offset:32
	global_load_dwordx4 v[24:27], v[0:1], off offset:48
	s_waitcnt vmcnt(0)
	v_mov_b32_e32 v115, v12
	v_mov_b32_e32 v114, v10
	v_mov_b32_e32 v12, v11
	v_mov_b32_e32 v117, v18
	v_mov_b32_e32 v116, v16
	v_mov_b32_e32 v18, v17
	v_mov_b32_e32 v119, v22
	v_mov_b32_e32 v118, v20
	v_mov_b32_e32 v22, v21
	v_mov_b32_e32 v121, v26
	v_mov_b32_e32 v120, v24
	v_mov_b32_e32 v26, v25
